# gate/up SwiGLU epilogue list-scheduled so exp/rcp/rsq interleave with the packed VALU ops (on top of the HGRN packed+interleaved gate block)
# baseline (speedup 1.0000x reference)
; __device__ __forceinline__ unsigned pk2(float lo, float hi) { unsigned r; asm("v_cvt_pk_bf16_f32 %0, %1, %2" : "=v"(r) : "v"(lo), "v"(hi)); return r; }
; __device__ __forceinline__ float sigmoidf_(float v) { return __builtin_amdgcn_rcpf(1.0f + fexp(-v)); }
; __device__ __forceinline__ void row_rstd8(const ssq_t* ss, int row0, float (&r)[8]) {
;     ssq_t sv[8];
; #pragma unroll
;     for (int k = 0; k < 8; ++k) sv[k] = ss[row0 + (k >> 2) * 128 + (k & 3) * 16];
;     asm volatile("" ::: "memory");
; #pragma unroll
;     for (int k = 0; k < 8; ++k) r[k] = rsqrtf((float)sv[k] * (1.0f / SSQ_SCALE) * (1.0f / D) + EPS);
; }
;     __device__ __forceinline__ bool operator()(f32x4 (&acc)[2][2][4][2], const pg8::Unit& u, int wr, int wc, int fr, int fq) const {
;         const int row0 = u.pm * 256 + wr * 64 + fr, col0 = u.pn * 128 + wc * 32 + 8 * fq;
;         float rr[8]; row_rstd8(ss, row0, rr);
; #pragma unroll
;         for (int ai = 0; ai < 2; ++ai)
; #pragma unroll
;             for (int m = 0; m < 4; ++m) {
;                 const int row = row0 + ai * 128 + m * 16; const float r = rr[ai * 4 + m];
;                 float o[8];
; #pragma unroll
;                 for (int n = 0; n < 2; ++n)
; #pragma unroll
;                     for (int j = 0; j < 4; ++j) { const float gv = acc[ai][0][m][n][j] * r, uv = acc[ai][1][m][n][j] * r; o[n * 4 + j] = gv * sigmoidf_(gv) * uv; }
;                 u32x4 w; w.x = pk2(o[0], o[1]); w.y = pk2(o[2], o[3]); w.z = pk2(o[4], o[5]); w.w = pk2(o[6], o[7]);
;                 *(u32x4*)(act + (size_t)row * FF + col0) = w;
;             }
.LBB0_97:
	v_lshl_add_u32 v140, s35, 8, v151
	v_readlane_b32 s6, v255, 31
	v_ashrrev_i32_e32 v141, 31, v140
	v_readlane_b32 s7, v255, 32
	v_lshl_or_b32 v156, s34, 7, v155
	v_ashrrev_i32_e32 v157, 31, v156
	v_lshl_add_u64 v[142:143], v[140:141], 3, s[6:7]
	global_load_dwordx2 v[160:161], v[142:143], off
	global_load_dwordx2 v[162:163], v[142:143], off offset:128
	global_load_dwordx2 v[164:165], v[142:143], off offset:256
	global_load_dwordx2 v[166:167], v[142:143], off offset:384
	global_load_dwordx2 v[146:147], v[142:143], off offset:1024
	global_load_dwordx2 v[148:149], v[142:143], off offset:1152
	global_load_dwordx2 v[144:145], v[142:143], off offset:1280
	s_nop 0
	global_load_dwordx2 v[142:143], v[142:143], off offset:1408
	v_lshlrev_b64 v[156:157], 1, v[156:157]
	v_lshl_add_u64 v[156:157], v[156:157], 0, s[90:91]
	v_mad_i64_i32 v[156:157], s[6:7], v140, s37, v[156:157]
	v_mov_b32_e32 v140, 1.0
	v_mov_b32_e32 v141, 1.0
	v_pk_mul_f32 v[122:123], v[122:123], v[126:127]
	v_pk_mul_f32 v[124:125], v[124:125], v[128:129]
	v_pk_mul_f32 v[114:115], v[114:115], v[118:119]
	v_pk_mul_f32 v[116:117], v[116:117], v[120:121]
	v_pk_mul_f32 v[106:107], v[106:107], v[110:111]
	v_pk_mul_f32 v[108:109], v[108:109], v[112:113]
	v_pk_mul_f32 v[98:99], v[98:99], v[102:103]
	v_pk_mul_f32 v[100:101], v[100:101], v[104:105]
	v_pk_mul_f32 v[90:91], v[90:91], v[94:95]
	v_pk_mul_f32 v[92:93], v[92:93], v[96:97]
	v_pk_mul_f32 v[82:83], v[82:83], v[86:87]
	v_pk_mul_f32 v[84:85], v[84:85], v[88:89]
	v_pk_mul_f32 v[74:75], v[74:75], v[78:79]
	v_pk_mul_f32 v[76:77], v[76:77], v[80:81]
	v_pk_mul_f32 v[66:67], v[66:67], v[70:71]
	v_pk_mul_f32 v[68:69], v[68:69], v[72:73]
	v_pk_mul_f32 v[58:59], v[58:59], v[62:63]
	v_pk_mul_f32 v[60:61], v[60:61], v[64:65]
	v_pk_mul_f32 v[50:51], v[50:51], v[54:55]
	v_pk_mul_f32 v[52:53], v[52:53], v[56:57]
	v_pk_mul_f32 v[42:43], v[42:43], v[46:47]
	v_pk_mul_f32 v[44:45], v[44:45], v[48:49]
	v_pk_mul_f32 v[34:35], v[34:35], v[38:39]
	v_pk_mul_f32 v[36:37], v[36:37], v[40:41]
	v_pk_mul_f32 v[26:27], v[26:27], v[30:31]
	v_pk_mul_f32 v[28:29], v[28:29], v[32:33]
	v_pk_mul_f32 v[18:19], v[18:19], v[22:23]
	v_pk_mul_f32 v[20:21], v[20:21], v[24:25]
	v_pk_mul_f32 v[10:11], v[10:11], v[14:15]
	v_pk_mul_f32 v[12:13], v[12:13], v[16:17]
	v_pk_mul_f32 v[2:3], v[2:3], v[6:7]
	v_pk_mul_f32 v[4:5], v[4:5], v[8:9]
	s_mov_b32 s6, 0x2c000
	s_mov_b32 s7, 0
	s_waitcnt vmcnt(0)
	v_ffbh_u32_e32 v150, v161
	v_min_u32_e32 v150, 32, v150
	v_lshlrev_b64 v[160:161], v150, v[160:161]
	v_min_u32_e32 v152, 1, v160
	v_or_b32_e32 v152, v161, v152
	v_cvt_f32_u32_e32 v152, v152
	v_sub_u32_e32 v150, 32, v150
	v_ldexp_f32 v152, v152, v150
	v_mul_f32_e32 v152, 0x33800000, v152
	v_fmamk_f32 v152, v152, 0x3a000000, v218
	v_rsq_f32_e32 v160, v152
	v_ffbh_u32_e32 v150, v163
	v_min_u32_e32 v150, 32, v150
	v_lshlrev_b64 v[162:163], v150, v[162:163]
	v_min_u32_e32 v152, 1, v162
	v_or_b32_e32 v152, v163, v152
	v_cvt_f32_u32_e32 v152, v152
	v_sub_u32_e32 v150, 32, v150
	v_ldexp_f32 v152, v152, v150
	v_mul_f32_e32 v152, 0x33800000, v152
	v_fmamk_f32 v152, v152, 0x3a000000, v218
	v_rsq_f32_e32 v162, v152
	v_ffbh_u32_e32 v150, v165
	v_min_u32_e32 v150, 32, v150
	v_lshlrev_b64 v[164:165], v150, v[164:165]
	v_min_u32_e32 v152, 1, v164
	v_or_b32_e32 v152, v165, v152
	v_cvt_f32_u32_e32 v152, v152
	v_sub_u32_e32 v150, 32, v150
	v_ldexp_f32 v152, v152, v150
	v_mul_f32_e32 v152, 0x33800000, v152
	v_fmamk_f32 v152, v152, 0x3a000000, v218
	v_rsq_f32_e32 v164, v152
	v_ffbh_u32_e32 v150, v167
	v_min_u32_e32 v150, 32, v150
	v_lshlrev_b64 v[166:167], v150, v[166:167]
	v_min_u32_e32 v152, 1, v166
	v_or_b32_e32 v152, v167, v152
	v_cvt_f32_u32_e32 v152, v152
	v_sub_u32_e32 v150, 32, v150
	v_ldexp_f32 v152, v152, v150
	v_mul_f32_e32 v152, 0x33800000, v152
	v_fmamk_f32 v152, v152, 0x3a000000, v218
	v_rsq_f32_e32 v166, v152
	v_ffbh_u32_e32 v150, v147
	v_min_u32_e32 v150, 32, v150
	v_lshlrev_b64 v[146:147], v150, v[146:147]
	v_min_u32_e32 v152, 1, v146
	v_or_b32_e32 v152, v147, v152
	v_cvt_f32_u32_e32 v152, v152
	v_sub_u32_e32 v150, 32, v150
	v_ldexp_f32 v152, v152, v150
	v_mul_f32_e32 v152, 0x33800000, v152
	v_fmamk_f32 v152, v152, 0x3a000000, v218
	v_rsq_f32_e32 v146, v152
	v_ffbh_u32_e32 v150, v149
	v_min_u32_e32 v150, 32, v150
	v_lshlrev_b64 v[148:149], v150, v[148:149]
	v_min_u32_e32 v152, 1, v148
	v_or_b32_e32 v152, v149, v152
	v_cvt_f32_u32_e32 v152, v152
	v_sub_u32_e32 v150, 32, v150
	v_ldexp_f32 v152, v152, v150
	v_mul_f32_e32 v152, 0x33800000, v152
	v_fmamk_f32 v152, v152, 0x3a000000, v218
	v_rsq_f32_e32 v148, v152
	v_ffbh_u32_e32 v150, v145
	v_min_u32_e32 v150, 32, v150
	v_lshlrev_b64 v[144:145], v150, v[144:145]
	v_min_u32_e32 v152, 1, v144
	v_or_b32_e32 v152, v145, v152
	v_cvt_f32_u32_e32 v152, v152
	v_sub_u32_e32 v150, 32, v150
	v_ldexp_f32 v152, v152, v150
	v_mul_f32_e32 v152, 0x33800000, v152
	v_fmamk_f32 v152, v152, 0x3a000000, v218
	v_rsq_f32_e32 v144, v152
	v_ffbh_u32_e32 v150, v143
	v_min_u32_e32 v150, 32, v150
	v_lshlrev_b64 v[142:143], v150, v[142:143]
	v_min_u32_e32 v152, 1, v142
	v_or_b32_e32 v152, v143, v152
	v_cvt_f32_u32_e32 v152, v152
	v_sub_u32_e32 v150, 32, v150
	v_ldexp_f32 v152, v152, v150
	v_mul_f32_e32 v150, 0xbfb8aa3b, v160
	v_pk_mul_f32 v[126:127], v[126:127], v[150:151] op_sel_hi:[1,0]
	v_pk_mul_f32 v[128:129], v[128:129], v[150:151] op_sel_hi:[1,0]
	v_exp_f32_e32 v126, v126
	v_pk_mul_f32 v[118:119], v[118:119], v[150:151] op_sel_hi:[1,0]
	v_pk_mul_f32 v[120:121], v[120:121], v[150:151] op_sel_hi:[1,0]
	v_exp_f32_e32 v127, v127
	v_mul_f32_e32 v150, 0xbfb8aa3b, v162
	v_mul_f32_e32 v152, 0x33800000, v152
	v_exp_f32_e32 v128, v128
	v_pk_mul_f32 v[110:111], v[110:111], v[150:151] op_sel_hi:[1,0]
; __device__ __forceinline__ unsigned pk2(float lo, float hi) { unsigned r; asm("v_cvt_pk_bf16_f32 %0, %1, %2" : "=v"(r) : "v"(lo), "v"(hi)); return r; }
; __device__ __forceinline__ float sigmoidf_(float v) { return __builtin_amdgcn_rcpf(1.0f + fexp(-v)); }
;     __device__ __forceinline__ bool operator()(f32x4 (&acc)[2][2][4][2], const pg8::Unit& u, int wr, int wc, int fr, int fq) const {
;     ...
;                 const int row = row0 + ai * 128 + m * 16; const float r = rr[ai * 4 + m];
;                 float o[8];
; #pragma unroll
;                 for (int n = 0; n < 2; ++n)
; #pragma unroll
;                     for (int j = 0; j < 4; ++j) { const float gv = acc[ai][0][m][n][j] * r, uv = acc[ai][1][m][n][j] * r; o[n * 4 + j] = gv * sigmoidf_(gv) * uv; }
;                 u32x4 w; w.x = pk2(o[0], o[1]); w.y = pk2(o[2], o[3]); w.z = pk2(o[4], o[5]); w.w = pk2(o[6], o[7]);
;                 *(u32x4*)(act + (size_t)row * FF + col0) = w;
	v_pk_mul_f32 v[112:113], v[112:113], v[150:151] op_sel_hi:[1,0]
	v_exp_f32_e32 v129, v129
	v_pk_mul_f32 v[102:103], v[102:103], v[150:151] op_sel_hi:[1,0]
	v_pk_mul_f32 v[104:105], v[104:105], v[150:151] op_sel_hi:[1,0]
	v_exp_f32_e32 v118, v118
	v_fmamk_f32 v152, v152, 0x3a000000, v218
	v_mul_f32_e32 v150, 0xbfb8aa3b, v164
	v_exp_f32_e32 v119, v119
	v_pk_mul_f32 v[94:95], v[94:95], v[150:151] op_sel_hi:[1,0]
	v_pk_mul_f32 v[96:97], v[96:97], v[150:151] op_sel_hi:[1,0]
	v_exp_f32_e32 v120, v120
	v_pk_mul_f32 v[86:87], v[86:87], v[150:151] op_sel_hi:[1,0]
	v_pk_mul_f32 v[88:89], v[88:89], v[150:151] op_sel_hi:[1,0]
	v_exp_f32_e32 v121, v121
	v_pk_add_f32 v[126:127], v[126:127], v[140:141]
	v_pk_add_f32 v[128:129], v[128:129], v[140:141]
	v_exp_f32_e32 v110, v110
	v_pk_add_f32 v[118:119], v[118:119], v[140:141]
	v_pk_add_f32 v[120:121], v[120:121], v[140:141]
	v_exp_f32_e32 v111, v111
	v_mul_f32_e32 v150, 0xbfb8aa3b, v166
	v_pk_mul_f32 v[78:79], v[78:79], v[150:151] op_sel_hi:[1,0]
	v_exp_f32_e32 v112, v112
	v_pk_mul_f32 v[80:81], v[80:81], v[150:151] op_sel_hi:[1,0]
	v_pk_mul_f32 v[70:71], v[70:71], v[150:151] op_sel_hi:[1,0]
	v_exp_f32_e32 v113, v113
	v_pk_mul_f32 v[72:73], v[72:73], v[150:151] op_sel_hi:[1,0]
	v_pk_add_f32 v[110:111], v[110:111], v[140:141]
	v_exp_f32_e32 v102, v102
	v_pk_add_f32 v[112:113], v[112:113], v[140:141]
	v_mul_f32_e32 v150, 0xbfb8aa3b, v146
	v_exp_f32_e32 v103, v103
	v_pk_mul_f32 v[62:63], v[62:63], v[150:151] op_sel_hi:[1,0]
	v_pk_add_f32 v[102:103], v[102:103], v[140:141]
	v_exp_f32_e32 v104, v104
	v_pk_mul_f32 v[64:65], v[64:65], v[150:151] op_sel_hi:[1,0]
	v_pk_mul_f32 v[54:55], v[54:55], v[150:151] op_sel_hi:[1,0]
	v_exp_f32_e32 v105, v105
	v_pk_mul_f32 v[56:57], v[56:57], v[150:151] op_sel_hi:[1,0]
	v_pk_add_f32 v[104:105], v[104:105], v[140:141]
	v_rsq_f32_e32 v142, v152
	v_mul_f32_e32 v152, v160, v160
	v_pk_mul_f32 v[122:123], v[122:123], v[152:153] op_sel_hi:[1,0]
	v_exp_f32_e32 v94, v94
	v_pk_mul_f32 v[124:125], v[124:125], v[152:153] op_sel_hi:[1,0]
	v_pk_mul_f32 v[114:115], v[114:115], v[152:153] op_sel_hi:[1,0]
	v_exp_f32_e32 v95, v95
	v_pk_mul_f32 v[116:117], v[116:117], v[152:153] op_sel_hi:[1,0]
	v_pk_add_f32 v[94:95], v[94:95], v[140:141]
	v_exp_f32_e32 v96, v96
	v_mul_f32_e32 v150, 0xbfb8aa3b, v148
	v_mul_f32_e32 v152, v162, v162
	v_exp_f32_e32 v97, v97
	v_pk_mul_f32 v[46:47], v[46:47], v[150:151] op_sel_hi:[1,0]
	v_pk_add_f32 v[96:97], v[96:97], v[140:141]
	v_exp_f32_e32 v86, v86
	v_pk_mul_f32 v[48:49], v[48:49], v[150:151] op_sel_hi:[1,0]
	v_pk_mul_f32 v[38:39], v[38:39], v[150:151] op_sel_hi:[1,0]
	v_exp_f32_e32 v87, v87
	v_pk_mul_f32 v[40:41], v[40:41], v[150:151] op_sel_hi:[1,0]
	v_pk_add_f32 v[86:87], v[86:87], v[140:141]
	v_exp_f32_e32 v88, v88
	v_pk_mul_f32 v[106:107], v[106:107], v[152:153] op_sel_hi:[1,0]
	v_pk_mul_f32 v[108:109], v[108:109], v[152:153] op_sel_hi:[1,0]
	v_exp_f32_e32 v89, v89
	v_pk_mul_f32 v[98:99], v[98:99], v[152:153] op_sel_hi:[1,0]
	v_pk_add_f32 v[88:89], v[88:89], v[140:141]
	v_rcp_f32_e32 v126, v126
	v_pk_mul_f32 v[100:101], v[100:101], v[152:153] op_sel_hi:[1,0]
	v_mul_f32_e32 v150, 0xbfb8aa3b, v144
	v_rcp_f32_e32 v127, v127
	v_mul_f32_e32 v152, v164, v164
	v_pk_mul_f32 v[122:123], v[122:123], v[126:127]
	v_rcp_f32_e32 v128, v128
	v_cvt_pk_bf16_f32 v126, v122, v123
	v_pk_mul_f32 v[30:31], v[30:31], v[150:151] op_sel_hi:[1,0]
	v_rcp_f32_e32 v129, v129
	v_pk_mul_f32 v[32:33], v[32:33], v[150:151] op_sel_hi:[1,0]
	v_pk_mul_f32 v[124:125], v[124:125], v[128:129]
	v_rcp_f32_e32 v118, v118
	v_cvt_pk_bf16_f32 v127, v124, v125
	v_pk_mul_f32 v[22:23], v[22:23], v[150:151] op_sel_hi:[1,0]
	v_rcp_f32_e32 v119, v119
	v_pk_mul_f32 v[24:25], v[24:25], v[150:151] op_sel_hi:[1,0]
	v_pk_mul_f32 v[114:115], v[114:115], v[118:119]
	v_rcp_f32_e32 v120, v120
	v_cvt_pk_bf16_f32 v128, v114, v115
	v_pk_mul_f32 v[90:91], v[90:91], v[152:153] op_sel_hi:[1,0]
	v_rcp_f32_e32 v121, v121
	v_pk_mul_f32 v[92:93], v[92:93], v[152:153] op_sel_hi:[1,0]
	v_pk_mul_f32 v[116:117], v[116:117], v[120:121]
	v_exp_f32_e32 v78, v78
	v_cvt_pk_bf16_f32 v129, v116, v117
	global_store_dwordx4 v[156:157], v[126:129], off
	v_exp_f32_e32 v79, v79
	v_lshl_add_u64 v[156:157], v[156:157], 0, s[6:7]
	v_pk_add_f32 v[78:79], v[78:79], v[140:141]
	v_exp_f32_e32 v80, v80
	v_pk_mul_f32 v[82:83], v[82:83], v[152:153] op_sel_hi:[1,0]
	v_pk_mul_f32 v[84:85], v[84:85], v[152:153] op_sel_hi:[1,0]
	v_exp_f32_e32 v81, v81
	v_mul_f32_e32 v150, 0xbfb8aa3b, v142
	v_pk_add_f32 v[80:81], v[80:81], v[140:141]
	v_exp_f32_e32 v70, v70
	v_mul_f32_e32 v152, v166, v166
	v_pk_mul_f32 v[14:15], v[14:15], v[150:151] op_sel_hi:[1,0]
	v_exp_f32_e32 v71, v71
	v_pk_mul_f32 v[16:17], v[16:17], v[150:151] op_sel_hi:[1,0]
	v_pk_add_f32 v[70:71], v[70:71], v[140:141]
	v_exp_f32_e32 v72, v72
	v_pk_mul_f32 v[6:7], v[6:7], v[150:151] op_sel_hi:[1,0]
	v_pk_mul_f32 v[8:9], v[8:9], v[150:151] op_sel_hi:[1,0]
	v_exp_f32_e32 v73, v73
	v_pk_mul_f32 v[74:75], v[74:75], v[152:153] op_sel_hi:[1,0]
	v_pk_add_f32 v[72:73], v[72:73], v[140:141]
	v_rcp_f32_e32 v110, v110
	v_pk_mul_f32 v[76:77], v[76:77], v[152:153] op_sel_hi:[1,0]
	v_pk_mul_f32 v[66:67], v[66:67], v[152:153] op_sel_hi:[1,0]
	v_rcp_f32_e32 v111, v111
	v_pk_mul_f32 v[68:69], v[68:69], v[152:153] op_sel_hi:[1,0]
	v_pk_mul_f32 v[106:107], v[106:107], v[110:111]
	v_rcp_f32_e32 v112, v112
	v_cvt_pk_bf16_f32 v110, v106, v107
	v_mul_f32_e32 v152, v146, v146
	v_rcp_f32_e32 v113, v113
	v_pk_mul_f32 v[58:59], v[58:59], v[152:153] op_sel_hi:[1,0]
	v_pk_mul_f32 v[108:109], v[108:109], v[112:113]
	v_rcp_f32_e32 v102, v102
	v_cvt_pk_bf16_f32 v111, v108, v109
	v_pk_mul_f32 v[60:61], v[60:61], v[152:153] op_sel_hi:[1,0]
; __device__ __forceinline__ unsigned pk2(float lo, float hi) { unsigned r; asm("v_cvt_pk_bf16_f32 %0, %1, %2" : "=v"(r) : "v"(lo), "v"(hi)); return r; }
; __device__ __forceinline__ float sigmoidf_(float v) { return __builtin_amdgcn_rcpf(1.0f + fexp(-v)); }
; #define PG8_BAR __builtin_amdgcn_s_barrier()
; template <class Epi, class Sched, bool ALIGN_EPI = true, bool SP2 = true>
; __device__ __forceinline__ void gemm_phase(LAS unsigned char* lds, const Gemm g, const Sched& S, const Epi& E) {
;     ...
;         if constexpr (ALIGN_EPI) { if (wr == 0) PG8_BAR; }
;         const bool keep = E(acc, cur, wr, wc, fr, fq);
;         if (!has_next) break;
;         if (!keep) {
; #pragma unroll
;         for (int a = 0; a < 2; ++a)
; #pragma unroll
;             for (int b = 0; b < 2; ++b)
; #pragma unroll
;                 for (int m = 0; m < 4; ++m)
; #pragma unroll
;                     for (int n = 0; n < 2; ++n) acc[a][b][m][n] = (f32x4){0.f, 0.f, 0.f, 0.f};
;         }
;         cur = nxt; cA = nA; cB = nB; ++ui;
;         if constexpr (ALIGN_EPI) { if (wr == 1) PG8_BAR; }
;     __device__ __forceinline__ bool operator()(f32x4 (&acc)[2][2][4][2], const pg8::Unit& u, int wr, int wc, int fr, int fq) const {
;     ...
;                 const int row = row0 + ai * 128 + m * 16; const float r = rr[ai * 4 + m];
;                 float o[8];
; #pragma unroll
;                 for (int n = 0; n < 2; ++n)
; #pragma unroll
;                     for (int j = 0; j < 4; ++j) { const float gv = acc[ai][0][m][n][j] * r, uv = acc[ai][1][m][n][j] * r; o[n * 4 + j] = gv * sigmoidf_(gv) * uv; }
;                 u32x4 w; w.x = pk2(o[0], o[1]); w.y = pk2(o[2], o[3]); w.z = pk2(o[4], o[5]); w.w = pk2(o[6], o[7]);
;                 *(u32x4*)(act + (size_t)row * FF + col0) = w;
	v_rcp_f32_e32 v103, v103
	v_pk_mul_f32 v[50:51], v[50:51], v[152:153] op_sel_hi:[1,0]
	v_pk_mul_f32 v[98:99], v[98:99], v[102:103]
	v_rcp_f32_e32 v104, v104
	v_cvt_pk_bf16_f32 v112, v98, v99
	v_pk_mul_f32 v[52:53], v[52:53], v[152:153] op_sel_hi:[1,0]
	v_rcp_f32_e32 v105, v105
	v_mul_f32_e32 v152, v148, v148
	v_pk_mul_f32 v[100:101], v[100:101], v[104:105]
	v_exp_f32_e32 v62, v62
	v_cvt_pk_bf16_f32 v113, v100, v101
	global_store_dwordx4 v[156:157], v[110:113], off
	v_exp_f32_e32 v63, v63
	v_lshl_add_u64 v[156:157], v[156:157], 0, s[6:7]
	v_pk_add_f32 v[62:63], v[62:63], v[140:141]
	v_exp_f32_e32 v64, v64
	v_pk_mul_f32 v[42:43], v[42:43], v[152:153] op_sel_hi:[1,0]
	v_pk_mul_f32 v[44:45], v[44:45], v[152:153] op_sel_hi:[1,0]
	v_exp_f32_e32 v65, v65
	v_pk_mul_f32 v[34:35], v[34:35], v[152:153] op_sel_hi:[1,0]
	v_pk_add_f32 v[64:65], v[64:65], v[140:141]
	v_exp_f32_e32 v54, v54
	v_pk_mul_f32 v[36:37], v[36:37], v[152:153] op_sel_hi:[1,0]
	v_mul_f32_e32 v152, v144, v144
	v_exp_f32_e32 v55, v55
	v_pk_mul_f32 v[26:27], v[26:27], v[152:153] op_sel_hi:[1,0]
	v_pk_add_f32 v[54:55], v[54:55], v[140:141]
	v_exp_f32_e32 v56, v56
	v_pk_mul_f32 v[28:29], v[28:29], v[152:153] op_sel_hi:[1,0]
	v_pk_mul_f32 v[18:19], v[18:19], v[152:153] op_sel_hi:[1,0]
	v_exp_f32_e32 v57, v57
	v_pk_mul_f32 v[20:21], v[20:21], v[152:153] op_sel_hi:[1,0]
	v_pk_add_f32 v[56:57], v[56:57], v[140:141]
	v_rcp_f32_e32 v94, v94
	v_mul_f32_e32 v152, v142, v142
	v_pk_mul_f32 v[10:11], v[10:11], v[152:153] op_sel_hi:[1,0]
	v_rcp_f32_e32 v95, v95
	v_pk_mul_f32 v[12:13], v[12:13], v[152:153] op_sel_hi:[1,0]
	v_pk_mul_f32 v[90:91], v[90:91], v[94:95]
	v_rcp_f32_e32 v96, v96
	v_cvt_pk_bf16_f32 v94, v90, v91
	v_pk_mul_f32 v[2:3], v[2:3], v[152:153] op_sel_hi:[1,0]
	v_rcp_f32_e32 v97, v97
	v_pk_mul_f32 v[4:5], v[4:5], v[152:153] op_sel_hi:[1,0]
	v_pk_mul_f32 v[92:93], v[92:93], v[96:97]
	v_rcp_f32_e32 v86, v86
	v_cvt_pk_bf16_f32 v95, v92, v93
	v_rcp_f32_e32 v87, v87
	v_rcp_f32_e32 v88, v88
	v_pk_mul_f32 v[82:83], v[82:83], v[86:87]
	v_rcp_f32_e32 v89, v89
	v_cvt_pk_bf16_f32 v96, v82, v83
	v_pk_mul_f32 v[84:85], v[84:85], v[88:89]
	v_exp_f32_e32 v46, v46
	v_cvt_pk_bf16_f32 v97, v84, v85
	global_store_dwordx4 v[156:157], v[94:97], off
	v_exp_f32_e32 v47, v47
	v_lshl_add_u64 v[156:157], v[156:157], 0, s[6:7]
	v_pk_add_f32 v[46:47], v[46:47], v[140:141]
	v_exp_f32_e32 v48, v48
	s_mov_b32 s6, 0xdc000
	v_exp_f32_e32 v49, v49
	v_exp_f32_e32 v38, v38
	v_pk_add_f32 v[48:49], v[48:49], v[140:141]
	v_exp_f32_e32 v39, v39
	v_exp_f32_e32 v40, v40
	v_pk_add_f32 v[38:39], v[38:39], v[140:141]
	v_exp_f32_e32 v41, v41
	v_rcp_f32_e32 v78, v78
	v_pk_add_f32 v[40:41], v[40:41], v[140:141]
	v_rcp_f32_e32 v79, v79
	v_rcp_f32_e32 v80, v80
	v_pk_mul_f32 v[74:75], v[74:75], v[78:79]
	v_rcp_f32_e32 v81, v81
	v_cvt_pk_bf16_f32 v78, v74, v75
	v_pk_mul_f32 v[76:77], v[76:77], v[80:81]
	v_rcp_f32_e32 v70, v70
	v_cvt_pk_bf16_f32 v79, v76, v77
	v_rcp_f32_e32 v71, v71
	v_rcp_f32_e32 v72, v72
	v_pk_mul_f32 v[66:67], v[66:67], v[70:71]
	v_rcp_f32_e32 v73, v73
	v_cvt_pk_bf16_f32 v80, v66, v67
	v_pk_mul_f32 v[68:69], v[68:69], v[72:73]
	v_exp_f32_e32 v30, v30
	v_cvt_pk_bf16_f32 v81, v68, v69
	global_store_dwordx4 v[156:157], v[78:81], off
	v_exp_f32_e32 v31, v31
	v_lshl_add_u64 v[156:157], v[156:157], 0, s[6:7]
	v_pk_add_f32 v[30:31], v[30:31], v[140:141]
	v_exp_f32_e32 v32, v32
	s_mov_b32 s6, 0x2c000
	v_exp_f32_e32 v33, v33
	v_exp_f32_e32 v22, v22
	v_pk_add_f32 v[32:33], v[32:33], v[140:141]
	v_exp_f32_e32 v23, v23
	v_exp_f32_e32 v24, v24
	v_pk_add_f32 v[22:23], v[22:23], v[140:141]
	v_exp_f32_e32 v25, v25
	v_rcp_f32_e32 v62, v62
	v_pk_add_f32 v[24:25], v[24:25], v[140:141]
	v_rcp_f32_e32 v63, v63
	v_rcp_f32_e32 v64, v64
	v_pk_mul_f32 v[58:59], v[58:59], v[62:63]
	v_rcp_f32_e32 v65, v65
	v_cvt_pk_bf16_f32 v62, v58, v59
	v_pk_mul_f32 v[60:61], v[60:61], v[64:65]
	v_rcp_f32_e32 v54, v54
	v_cvt_pk_bf16_f32 v63, v60, v61
	v_rcp_f32_e32 v55, v55
	v_rcp_f32_e32 v56, v56
	v_pk_mul_f32 v[50:51], v[50:51], v[54:55]
	v_rcp_f32_e32 v57, v57
	v_cvt_pk_bf16_f32 v64, v50, v51
	v_pk_mul_f32 v[52:53], v[52:53], v[56:57]
	v_exp_f32_e32 v14, v14
	v_cvt_pk_bf16_f32 v65, v52, v53
	global_store_dwordx4 v[156:157], v[62:65], off
	v_exp_f32_e32 v15, v15
	v_lshl_add_u64 v[156:157], v[156:157], 0, s[6:7]
	v_pk_add_f32 v[14:15], v[14:15], v[140:141]
	v_exp_f32_e32 v16, v16
	v_exp_f32_e32 v17, v17
	v_exp_f32_e32 v6, v6
	v_pk_add_f32 v[16:17], v[16:17], v[140:141]
	v_exp_f32_e32 v7, v7
	v_exp_f32_e32 v8, v8
	v_pk_add_f32 v[6:7], v[6:7], v[140:141]
	v_exp_f32_e32 v9, v9
	v_rcp_f32_e32 v46, v46
	v_pk_add_f32 v[8:9], v[8:9], v[140:141]
	v_rcp_f32_e32 v47, v47
	v_rcp_f32_e32 v48, v48
	v_pk_mul_f32 v[42:43], v[42:43], v[46:47]
	v_rcp_f32_e32 v49, v49
	v_cvt_pk_bf16_f32 v46, v42, v43
	v_pk_mul_f32 v[44:45], v[44:45], v[48:49]
	v_rcp_f32_e32 v38, v38
	v_cvt_pk_bf16_f32 v47, v44, v45
	v_rcp_f32_e32 v39, v39
	v_rcp_f32_e32 v40, v40
	v_pk_mul_f32 v[34:35], v[34:35], v[38:39]
	v_rcp_f32_e32 v41, v41
	v_cvt_pk_bf16_f32 v48, v34, v35
	v_pk_mul_f32 v[36:37], v[36:37], v[40:41]
	v_rcp_f32_e32 v30, v30
	v_cvt_pk_bf16_f32 v49, v36, v37
	global_store_dwordx4 v[156:157], v[46:49], off
	v_rcp_f32_e32 v31, v31
	v_lshl_add_u64 v[156:157], v[156:157], 0, s[6:7]
	v_pk_mul_f32 v[26:27], v[26:27], v[30:31]
	v_rcp_f32_e32 v32, v32
	v_cvt_pk_bf16_f32 v30, v26, v27
	v_rcp_f32_e32 v33, v33
	v_rcp_f32_e32 v22, v22
	v_pk_mul_f32 v[28:29], v[28:29], v[32:33]
	v_rcp_f32_e32 v23, v23
	v_cvt_pk_bf16_f32 v31, v28, v29
	v_pk_mul_f32 v[18:19], v[18:19], v[22:23]
	v_rcp_f32_e32 v24, v24
	v_cvt_pk_bf16_f32 v32, v18, v19
	v_rcp_f32_e32 v25, v25
	v_rcp_f32_e32 v14, v14
	v_pk_mul_f32 v[20:21], v[20:21], v[24:25]
	v_rcp_f32_e32 v15, v15
	v_cvt_pk_bf16_f32 v33, v20, v21
	global_store_dwordx4 v[156:157], v[30:33], off
	v_rcp_f32_e32 v16, v16
	v_pk_mul_f32 v[10:11], v[10:11], v[14:15]
	v_lshl_add_u64 v[156:157], v[156:157], 0, s[6:7]
	v_rcp_f32_e32 v17, v17
	v_cvt_pk_bf16_f32 v14, v10, v11
	v_pk_mul_f32 v[12:13], v[12:13], v[16:17]
	v_rcp_f32_e32 v6, v6
	v_cvt_pk_bf16_f32 v15, v12, v13
	v_rcp_f32_e32 v7, v7
	v_rcp_f32_e32 v8, v8
	v_pk_mul_f32 v[2:3], v[2:3], v[6:7]
	v_rcp_f32_e32 v9, v9
	v_cvt_pk_bf16_f32 v16, v2, v3
	v_pk_mul_f32 v[4:5], v[4:5], v[8:9]
	s_nop 0
	v_cvt_pk_bf16_f32 v17, v4, v5
	global_store_dwordx4 v[156:157], v[14:17], off
	s_mov_b64 s[6:7], -1
	s_andn2_b64 vcc, exec, s[0:1]
	s_cbranch_vccnz .LBB0_90
	s_andn2_b64 vcc, exec, s[4:5]
	s_cbranch_vccnz .LBB0_89
	s_barrier
	s_branch .LBB0_89

; __device__ __forceinline__ unsigned pk2(float lo, float hi) { unsigned r; asm("v_cvt_pk_bf16_f32 %0, %1, %2" : "=v"(r) : "v"(lo), "v"(hi)); return r; }
; __device__ __forceinline__ float sigmoidf_(float v) { return __builtin_amdgcn_rcpf(1.0f + fexp(-v)); }
; __device__ __forceinline__ void row_rstd8(const ssq_t* ss, int row0, float (&r)[8]) {
;     ssq_t sv[8];
; #pragma unroll
;     for (int k = 0; k < 8; ++k) sv[k] = ss[row0 + (k >> 2) * 128 + (k & 3) * 16];
;     asm volatile("" ::: "memory");
; #pragma unroll
;     for (int k = 0; k < 8; ++k) r[k] = rsqrtf((float)sv[k] * (1.0f / SSQ_SCALE) * (1.0f / D) + EPS);
; }
;     __device__ __forceinline__ bool operator()(f32x4 (&acc)[2][2][4][2], const pg8::Unit& u, int wr, int wc, int fr, int fq) const {
;         const int row0 = u.pm * 256 + wr * 64 + fr, col0 = u.pn * 128 + wc * 32 + 8 * fq;
;         float rr[8]; row_rstd8(ss, row0, rr);
; #pragma unroll
;         for (int ai = 0; ai < 2; ++ai)
; #pragma unroll
;             for (int m = 0; m < 4; ++m) {
;                 const int row = row0 + ai * 128 + m * 16; const float r = rr[ai * 4 + m];
;                 float o[8];
; #pragma unroll
;                 for (int n = 0; n < 2; ++n)
; #pragma unroll
;                     for (int j = 0; j < 4; ++j) { const float gv = acc[ai][0][m][n][j] * r, uv = acc[ai][1][m][n][j] * r; o[n * 4 + j] = gv * sigmoidf_(gv) * uv; }
;                 u32x4 w; w.x = pk2(o[0], o[1]); w.y = pk2(o[2], o[3]); w.z = pk2(o[4], o[5]); w.w = pk2(o[6], o[7]);
;                 *(u32x4*)(act + (size_t)row * FF + col0) = w;
;             }
.LBB0_874:
	v_lshl_add_u32 v140, s57, 8, v151
	v_ashrrev_i32_e32 v141, 31, v140
	v_lshl_or_b32 v156, s56, 7, v155
	v_ashrrev_i32_e32 v157, 31, v156
	v_lshl_add_u64 v[142:143], v[140:141], 3, s[0:1]
	global_load_dwordx2 v[160:161], v[142:143], off
	global_load_dwordx2 v[162:163], v[142:143], off offset:128
	global_load_dwordx2 v[164:165], v[142:143], off offset:256
	global_load_dwordx2 v[166:167], v[142:143], off offset:384
	global_load_dwordx2 v[146:147], v[142:143], off offset:1024
	global_load_dwordx2 v[148:149], v[142:143], off offset:1152
	global_load_dwordx2 v[144:145], v[142:143], off offset:1280
	s_nop 0
	global_load_dwordx2 v[142:143], v[142:143], off offset:1408
	v_lshlrev_b64 v[156:157], 1, v[156:157]
	v_lshl_add_u64 v[156:157], v[156:157], 0, s[90:91]
	v_mad_i64_i32 v[156:157], s[4:5], v140, s37, v[156:157]
	v_mov_b32_e32 v140, 1.0
	v_mov_b32_e32 v141, 1.0
	v_pk_mul_f32 v[122:123], v[122:123], v[126:127]
	v_pk_mul_f32 v[124:125], v[124:125], v[128:129]
	v_pk_mul_f32 v[114:115], v[114:115], v[118:119]
	v_pk_mul_f32 v[116:117], v[116:117], v[120:121]
	v_pk_mul_f32 v[106:107], v[106:107], v[110:111]
	v_pk_mul_f32 v[108:109], v[108:109], v[112:113]
	v_pk_mul_f32 v[98:99], v[98:99], v[102:103]
	v_pk_mul_f32 v[100:101], v[100:101], v[104:105]
	v_pk_mul_f32 v[90:91], v[90:91], v[94:95]
	v_pk_mul_f32 v[92:93], v[92:93], v[96:97]
	v_pk_mul_f32 v[82:83], v[82:83], v[86:87]
	v_pk_mul_f32 v[84:85], v[84:85], v[88:89]
	v_pk_mul_f32 v[74:75], v[74:75], v[78:79]
	v_pk_mul_f32 v[76:77], v[76:77], v[80:81]
	v_pk_mul_f32 v[66:67], v[66:67], v[70:71]
	v_pk_mul_f32 v[68:69], v[68:69], v[72:73]
	v_pk_mul_f32 v[58:59], v[58:59], v[62:63]
	v_pk_mul_f32 v[60:61], v[60:61], v[64:65]
	v_pk_mul_f32 v[50:51], v[50:51], v[54:55]
	v_pk_mul_f32 v[52:53], v[52:53], v[56:57]
	v_pk_mul_f32 v[42:43], v[42:43], v[46:47]
	v_pk_mul_f32 v[44:45], v[44:45], v[48:49]
	v_pk_mul_f32 v[34:35], v[34:35], v[38:39]
	v_pk_mul_f32 v[36:37], v[36:37], v[40:41]
	v_pk_mul_f32 v[26:27], v[26:27], v[30:31]
	v_pk_mul_f32 v[28:29], v[28:29], v[32:33]
	v_pk_mul_f32 v[18:19], v[18:19], v[22:23]
	v_pk_mul_f32 v[20:21], v[20:21], v[24:25]
	v_pk_mul_f32 v[10:11], v[10:11], v[14:15]
	v_pk_mul_f32 v[12:13], v[12:13], v[16:17]
	v_pk_mul_f32 v[2:3], v[2:3], v[6:7]
	v_pk_mul_f32 v[4:5], v[4:5], v[8:9]
	s_mov_b32 s4, 0x2c000
	s_mov_b32 s5, 0
	s_waitcnt vmcnt(0)
	v_ffbh_u32_e32 v150, v161
	v_min_u32_e32 v150, 32, v150
	v_lshlrev_b64 v[160:161], v150, v[160:161]
	v_min_u32_e32 v152, 1, v160
	v_or_b32_e32 v152, v161, v152
	v_cvt_f32_u32_e32 v152, v152
	v_sub_u32_e32 v150, 32, v150
	v_ldexp_f32 v152, v152, v150
	v_mul_f32_e32 v152, 0x33800000, v152
	v_fmamk_f32 v152, v152, 0x3a000000, v218
	v_rsq_f32_e32 v160, v152
	v_ffbh_u32_e32 v150, v163
	v_min_u32_e32 v150, 32, v150
	v_lshlrev_b64 v[162:163], v150, v[162:163]
	v_min_u32_e32 v152, 1, v162
	v_or_b32_e32 v152, v163, v152
	v_cvt_f32_u32_e32 v152, v152
	v_sub_u32_e32 v150, 32, v150
	v_ldexp_f32 v152, v152, v150
	v_mul_f32_e32 v152, 0x33800000, v152
	v_fmamk_f32 v152, v152, 0x3a000000, v218
	v_rsq_f32_e32 v162, v152
	v_ffbh_u32_e32 v150, v165
	v_min_u32_e32 v150, 32, v150
	v_lshlrev_b64 v[164:165], v150, v[164:165]
	v_min_u32_e32 v152, 1, v164
	v_or_b32_e32 v152, v165, v152
	v_cvt_f32_u32_e32 v152, v152
	v_sub_u32_e32 v150, 32, v150
	v_ldexp_f32 v152, v152, v150
	v_mul_f32_e32 v152, 0x33800000, v152
	v_fmamk_f32 v152, v152, 0x3a000000, v218
	v_rsq_f32_e32 v164, v152
	v_ffbh_u32_e32 v150, v167
	v_min_u32_e32 v150, 32, v150
	v_lshlrev_b64 v[166:167], v150, v[166:167]
	v_min_u32_e32 v152, 1, v166
	v_or_b32_e32 v152, v167, v152
	v_cvt_f32_u32_e32 v152, v152
	v_sub_u32_e32 v150, 32, v150
	v_ldexp_f32 v152, v152, v150
	v_mul_f32_e32 v152, 0x33800000, v152
	v_fmamk_f32 v152, v152, 0x3a000000, v218
	v_rsq_f32_e32 v166, v152
	v_ffbh_u32_e32 v150, v147
	v_min_u32_e32 v150, 32, v150
	v_lshlrev_b64 v[146:147], v150, v[146:147]
	v_min_u32_e32 v152, 1, v146
	v_or_b32_e32 v152, v147, v152
	v_cvt_f32_u32_e32 v152, v152
	v_sub_u32_e32 v150, 32, v150
	v_ldexp_f32 v152, v152, v150
	v_mul_f32_e32 v152, 0x33800000, v152
	v_fmamk_f32 v152, v152, 0x3a000000, v218
	v_rsq_f32_e32 v146, v152
	v_ffbh_u32_e32 v150, v149
	v_min_u32_e32 v150, 32, v150
	v_lshlrev_b64 v[148:149], v150, v[148:149]
	v_min_u32_e32 v152, 1, v148
	v_or_b32_e32 v152, v149, v152
	v_cvt_f32_u32_e32 v152, v152
	v_sub_u32_e32 v150, 32, v150
	v_ldexp_f32 v152, v152, v150
	v_mul_f32_e32 v152, 0x33800000, v152
	v_fmamk_f32 v152, v152, 0x3a000000, v218
	v_rsq_f32_e32 v148, v152
	v_ffbh_u32_e32 v150, v145
	v_min_u32_e32 v150, 32, v150
	v_lshlrev_b64 v[144:145], v150, v[144:145]
	v_min_u32_e32 v152, 1, v144
	v_or_b32_e32 v152, v145, v152
	v_cvt_f32_u32_e32 v152, v152
	v_sub_u32_e32 v150, 32, v150
	v_ldexp_f32 v152, v152, v150
	v_mul_f32_e32 v152, 0x33800000, v152
	v_fmamk_f32 v152, v152, 0x3a000000, v218
	v_rsq_f32_e32 v144, v152
	v_ffbh_u32_e32 v150, v143
	v_min_u32_e32 v150, 32, v150
	v_lshlrev_b64 v[142:143], v150, v[142:143]
	v_min_u32_e32 v152, 1, v142
	v_or_b32_e32 v152, v143, v152
	v_cvt_f32_u32_e32 v152, v152
	v_sub_u32_e32 v150, 32, v150
	v_ldexp_f32 v152, v152, v150
	v_mul_f32_e32 v150, 0xbfb8aa3b, v160
	v_pk_mul_f32 v[126:127], v[126:127], v[150:151] op_sel_hi:[1,0]
	v_pk_mul_f32 v[128:129], v[128:129], v[150:151] op_sel_hi:[1,0]
	v_exp_f32_e32 v126, v126
	v_pk_mul_f32 v[118:119], v[118:119], v[150:151] op_sel_hi:[1,0]
	v_pk_mul_f32 v[120:121], v[120:121], v[150:151] op_sel_hi:[1,0]
	v_exp_f32_e32 v127, v127
	v_mul_f32_e32 v150, 0xbfb8aa3b, v162
	v_mul_f32_e32 v152, 0x33800000, v152
	v_exp_f32_e32 v128, v128
	v_pk_mul_f32 v[110:111], v[110:111], v[150:151] op_sel_hi:[1,0]
; __device__ __forceinline__ unsigned pk2(float lo, float hi) { unsigned r; asm("v_cvt_pk_bf16_f32 %0, %1, %2" : "=v"(r) : "v"(lo), "v"(hi)); return r; }
; __device__ __forceinline__ float sigmoidf_(float v) { return __builtin_amdgcn_rcpf(1.0f + fexp(-v)); }
;     __device__ __forceinline__ bool operator()(f32x4 (&acc)[2][2][4][2], const pg8::Unit& u, int wr, int wc, int fr, int fq) const {
;     ...
;                 const int row = row0 + ai * 128 + m * 16; const float r = rr[ai * 4 + m];
;                 float o[8];
; #pragma unroll
;                 for (int n = 0; n < 2; ++n)
; #pragma unroll
;                     for (int j = 0; j < 4; ++j) { const float gv = acc[ai][0][m][n][j] * r, uv = acc[ai][1][m][n][j] * r; o[n * 4 + j] = gv * sigmoidf_(gv) * uv; }
;                 u32x4 w; w.x = pk2(o[0], o[1]); w.y = pk2(o[2], o[3]); w.z = pk2(o[4], o[5]); w.w = pk2(o[6], o[7]);
;                 *(u32x4*)(act + (size_t)row * FF + col0) = w;
	v_pk_mul_f32 v[112:113], v[112:113], v[150:151] op_sel_hi:[1,0]
	v_exp_f32_e32 v129, v129
	v_pk_mul_f32 v[102:103], v[102:103], v[150:151] op_sel_hi:[1,0]
	v_pk_mul_f32 v[104:105], v[104:105], v[150:151] op_sel_hi:[1,0]
	v_exp_f32_e32 v118, v118
	v_fmamk_f32 v152, v152, 0x3a000000, v218
	v_mul_f32_e32 v150, 0xbfb8aa3b, v164
	v_exp_f32_e32 v119, v119
	v_pk_mul_f32 v[94:95], v[94:95], v[150:151] op_sel_hi:[1,0]
	v_pk_mul_f32 v[96:97], v[96:97], v[150:151] op_sel_hi:[1,0]
	v_exp_f32_e32 v120, v120
	v_pk_mul_f32 v[86:87], v[86:87], v[150:151] op_sel_hi:[1,0]
	v_pk_mul_f32 v[88:89], v[88:89], v[150:151] op_sel_hi:[1,0]
	v_exp_f32_e32 v121, v121
	v_pk_add_f32 v[126:127], v[126:127], v[140:141]
	v_pk_add_f32 v[128:129], v[128:129], v[140:141]
	v_exp_f32_e32 v110, v110
	v_pk_add_f32 v[118:119], v[118:119], v[140:141]
	v_pk_add_f32 v[120:121], v[120:121], v[140:141]
	v_exp_f32_e32 v111, v111
	v_mul_f32_e32 v150, 0xbfb8aa3b, v166
	v_pk_mul_f32 v[78:79], v[78:79], v[150:151] op_sel_hi:[1,0]
	v_exp_f32_e32 v112, v112
	v_pk_mul_f32 v[80:81], v[80:81], v[150:151] op_sel_hi:[1,0]
	v_pk_mul_f32 v[70:71], v[70:71], v[150:151] op_sel_hi:[1,0]
	v_exp_f32_e32 v113, v113
	v_pk_mul_f32 v[72:73], v[72:73], v[150:151] op_sel_hi:[1,0]
	v_pk_add_f32 v[110:111], v[110:111], v[140:141]
	v_exp_f32_e32 v102, v102
	v_pk_add_f32 v[112:113], v[112:113], v[140:141]
	v_mul_f32_e32 v150, 0xbfb8aa3b, v146
	v_exp_f32_e32 v103, v103
	v_pk_mul_f32 v[62:63], v[62:63], v[150:151] op_sel_hi:[1,0]
	v_pk_add_f32 v[102:103], v[102:103], v[140:141]
	v_exp_f32_e32 v104, v104
	v_pk_mul_f32 v[64:65], v[64:65], v[150:151] op_sel_hi:[1,0]
	v_pk_mul_f32 v[54:55], v[54:55], v[150:151] op_sel_hi:[1,0]
	v_exp_f32_e32 v105, v105
	v_pk_mul_f32 v[56:57], v[56:57], v[150:151] op_sel_hi:[1,0]
	v_pk_add_f32 v[104:105], v[104:105], v[140:141]
	v_rsq_f32_e32 v142, v152
	v_mul_f32_e32 v152, v160, v160
	v_pk_mul_f32 v[122:123], v[122:123], v[152:153] op_sel_hi:[1,0]
	v_exp_f32_e32 v94, v94
	v_pk_mul_f32 v[124:125], v[124:125], v[152:153] op_sel_hi:[1,0]
	v_pk_mul_f32 v[114:115], v[114:115], v[152:153] op_sel_hi:[1,0]
	v_exp_f32_e32 v95, v95
	v_pk_mul_f32 v[116:117], v[116:117], v[152:153] op_sel_hi:[1,0]
	v_pk_add_f32 v[94:95], v[94:95], v[140:141]
	v_exp_f32_e32 v96, v96
	v_mul_f32_e32 v150, 0xbfb8aa3b, v148
	v_mul_f32_e32 v152, v162, v162
	v_exp_f32_e32 v97, v97
	v_pk_mul_f32 v[46:47], v[46:47], v[150:151] op_sel_hi:[1,0]
	v_pk_add_f32 v[96:97], v[96:97], v[140:141]
	v_exp_f32_e32 v86, v86
	v_pk_mul_f32 v[48:49], v[48:49], v[150:151] op_sel_hi:[1,0]
	v_pk_mul_f32 v[38:39], v[38:39], v[150:151] op_sel_hi:[1,0]
	v_exp_f32_e32 v87, v87
	v_pk_mul_f32 v[40:41], v[40:41], v[150:151] op_sel_hi:[1,0]
	v_pk_add_f32 v[86:87], v[86:87], v[140:141]
	v_exp_f32_e32 v88, v88
	v_pk_mul_f32 v[106:107], v[106:107], v[152:153] op_sel_hi:[1,0]
	v_pk_mul_f32 v[108:109], v[108:109], v[152:153] op_sel_hi:[1,0]
	v_exp_f32_e32 v89, v89
	v_pk_mul_f32 v[98:99], v[98:99], v[152:153] op_sel_hi:[1,0]
	v_pk_add_f32 v[88:89], v[88:89], v[140:141]
	v_rcp_f32_e32 v126, v126
	v_pk_mul_f32 v[100:101], v[100:101], v[152:153] op_sel_hi:[1,0]
	v_mul_f32_e32 v150, 0xbfb8aa3b, v144
	v_rcp_f32_e32 v127, v127
	v_mul_f32_e32 v152, v164, v164
	v_pk_mul_f32 v[122:123], v[122:123], v[126:127]
	v_rcp_f32_e32 v128, v128
	v_cvt_pk_bf16_f32 v126, v122, v123
	v_pk_mul_f32 v[30:31], v[30:31], v[150:151] op_sel_hi:[1,0]
	v_rcp_f32_e32 v129, v129
	v_pk_mul_f32 v[32:33], v[32:33], v[150:151] op_sel_hi:[1,0]
	v_pk_mul_f32 v[124:125], v[124:125], v[128:129]
	v_rcp_f32_e32 v118, v118
	v_cvt_pk_bf16_f32 v127, v124, v125
	v_pk_mul_f32 v[22:23], v[22:23], v[150:151] op_sel_hi:[1,0]
	v_rcp_f32_e32 v119, v119
	v_pk_mul_f32 v[24:25], v[24:25], v[150:151] op_sel_hi:[1,0]
	v_pk_mul_f32 v[114:115], v[114:115], v[118:119]
	v_rcp_f32_e32 v120, v120
	v_cvt_pk_bf16_f32 v128, v114, v115
	v_pk_mul_f32 v[90:91], v[90:91], v[152:153] op_sel_hi:[1,0]
	v_rcp_f32_e32 v121, v121
	v_pk_mul_f32 v[92:93], v[92:93], v[152:153] op_sel_hi:[1,0]
	v_pk_mul_f32 v[116:117], v[116:117], v[120:121]
	v_exp_f32_e32 v78, v78
	v_cvt_pk_bf16_f32 v129, v116, v117
	global_store_dwordx4 v[156:157], v[126:129], off
	v_exp_f32_e32 v79, v79
	v_lshl_add_u64 v[156:157], v[156:157], 0, s[4:5]
	v_pk_add_f32 v[78:79], v[78:79], v[140:141]
	v_exp_f32_e32 v80, v80
	v_pk_mul_f32 v[82:83], v[82:83], v[152:153] op_sel_hi:[1,0]
	v_pk_mul_f32 v[84:85], v[84:85], v[152:153] op_sel_hi:[1,0]
	v_exp_f32_e32 v81, v81
	v_mul_f32_e32 v150, 0xbfb8aa3b, v142
	v_pk_add_f32 v[80:81], v[80:81], v[140:141]
	v_exp_f32_e32 v70, v70
	v_mul_f32_e32 v152, v166, v166
	v_pk_mul_f32 v[14:15], v[14:15], v[150:151] op_sel_hi:[1,0]
	v_exp_f32_e32 v71, v71
	v_pk_mul_f32 v[16:17], v[16:17], v[150:151] op_sel_hi:[1,0]
	v_pk_add_f32 v[70:71], v[70:71], v[140:141]
	v_exp_f32_e32 v72, v72
	v_pk_mul_f32 v[6:7], v[6:7], v[150:151] op_sel_hi:[1,0]
	v_pk_mul_f32 v[8:9], v[8:9], v[150:151] op_sel_hi:[1,0]
	v_exp_f32_e32 v73, v73
	v_pk_mul_f32 v[74:75], v[74:75], v[152:153] op_sel_hi:[1,0]
	v_pk_add_f32 v[72:73], v[72:73], v[140:141]
	v_rcp_f32_e32 v110, v110
	v_pk_mul_f32 v[76:77], v[76:77], v[152:153] op_sel_hi:[1,0]
	v_pk_mul_f32 v[66:67], v[66:67], v[152:153] op_sel_hi:[1,0]
	v_rcp_f32_e32 v111, v111
	v_pk_mul_f32 v[68:69], v[68:69], v[152:153] op_sel_hi:[1,0]
	v_pk_mul_f32 v[106:107], v[106:107], v[110:111]
	v_rcp_f32_e32 v112, v112
	v_cvt_pk_bf16_f32 v110, v106, v107
	v_mul_f32_e32 v152, v146, v146
	v_rcp_f32_e32 v113, v113
	v_pk_mul_f32 v[58:59], v[58:59], v[152:153] op_sel_hi:[1,0]
	v_pk_mul_f32 v[108:109], v[108:109], v[112:113]
	v_rcp_f32_e32 v102, v102
	v_cvt_pk_bf16_f32 v111, v108, v109
	v_pk_mul_f32 v[60:61], v[60:61], v[152:153] op_sel_hi:[1,0]
; __device__ __forceinline__ unsigned pk2(float lo, float hi) { unsigned r; asm("v_cvt_pk_bf16_f32 %0, %1, %2" : "=v"(r) : "v"(lo), "v"(hi)); return r; }
; __device__ __forceinline__ float sigmoidf_(float v) { return __builtin_amdgcn_rcpf(1.0f + fexp(-v)); }
; #define PG8_BAR __builtin_amdgcn_s_barrier()
; template <class Epi, class Sched, bool ALIGN_EPI = true, bool SP2 = true>
; __device__ __forceinline__ void gemm_phase(LAS unsigned char* lds, const Gemm g, const Sched& S, const Epi& E) {
;     ...
;         if constexpr (ALIGN_EPI) { if (wr == 0) PG8_BAR; }
;         const bool keep = E(acc, cur, wr, wc, fr, fq);
;         if (!has_next) break;
;         if (!keep) {
; #pragma unroll
;         for (int a = 0; a < 2; ++a)
; #pragma unroll
;             for (int b = 0; b < 2; ++b)
; #pragma unroll
;                 for (int m = 0; m < 4; ++m)
; #pragma unroll
;                     for (int n = 0; n < 2; ++n) acc[a][b][m][n] = (f32x4){0.f, 0.f, 0.f, 0.f};
;         }
;         cur = nxt; cA = nA; cB = nB; ++ui;
;         if constexpr (ALIGN_EPI) { if (wr == 1) PG8_BAR; }
;     __device__ __forceinline__ bool operator()(f32x4 (&acc)[2][2][4][2], const pg8::Unit& u, int wr, int wc, int fr, int fq) const {
;     ...
;                 const int row = row0 + ai * 128 + m * 16; const float r = rr[ai * 4 + m];
;                 float o[8];
; #pragma unroll
;                 for (int n = 0; n < 2; ++n)
; #pragma unroll
;                     for (int j = 0; j < 4; ++j) { const float gv = acc[ai][0][m][n][j] * r, uv = acc[ai][1][m][n][j] * r; o[n * 4 + j] = gv * sigmoidf_(gv) * uv; }
;                 u32x4 w; w.x = pk2(o[0], o[1]); w.y = pk2(o[2], o[3]); w.z = pk2(o[4], o[5]); w.w = pk2(o[6], o[7]);
;                 *(u32x4*)(act + (size_t)row * FF + col0) = w;
	v_rcp_f32_e32 v103, v103
	v_pk_mul_f32 v[50:51], v[50:51], v[152:153] op_sel_hi:[1,0]
	v_pk_mul_f32 v[98:99], v[98:99], v[102:103]
	v_rcp_f32_e32 v104, v104
	v_cvt_pk_bf16_f32 v112, v98, v99
	v_pk_mul_f32 v[52:53], v[52:53], v[152:153] op_sel_hi:[1,0]
	v_rcp_f32_e32 v105, v105
	v_mul_f32_e32 v152, v148, v148
	v_pk_mul_f32 v[100:101], v[100:101], v[104:105]
	v_exp_f32_e32 v62, v62
	v_cvt_pk_bf16_f32 v113, v100, v101
	global_store_dwordx4 v[156:157], v[110:113], off
	v_exp_f32_e32 v63, v63
	v_lshl_add_u64 v[156:157], v[156:157], 0, s[4:5]
	v_pk_add_f32 v[62:63], v[62:63], v[140:141]
	v_exp_f32_e32 v64, v64
	v_pk_mul_f32 v[42:43], v[42:43], v[152:153] op_sel_hi:[1,0]
	v_pk_mul_f32 v[44:45], v[44:45], v[152:153] op_sel_hi:[1,0]
	v_exp_f32_e32 v65, v65
	v_pk_mul_f32 v[34:35], v[34:35], v[152:153] op_sel_hi:[1,0]
	v_pk_add_f32 v[64:65], v[64:65], v[140:141]
	v_exp_f32_e32 v54, v54
	v_pk_mul_f32 v[36:37], v[36:37], v[152:153] op_sel_hi:[1,0]
	v_mul_f32_e32 v152, v144, v144
	v_exp_f32_e32 v55, v55
	v_pk_mul_f32 v[26:27], v[26:27], v[152:153] op_sel_hi:[1,0]
	v_pk_add_f32 v[54:55], v[54:55], v[140:141]
	v_exp_f32_e32 v56, v56
	v_pk_mul_f32 v[28:29], v[28:29], v[152:153] op_sel_hi:[1,0]
	v_pk_mul_f32 v[18:19], v[18:19], v[152:153] op_sel_hi:[1,0]
	v_exp_f32_e32 v57, v57
	v_pk_mul_f32 v[20:21], v[20:21], v[152:153] op_sel_hi:[1,0]
	v_pk_add_f32 v[56:57], v[56:57], v[140:141]
	v_rcp_f32_e32 v94, v94
	v_mul_f32_e32 v152, v142, v142
	v_pk_mul_f32 v[10:11], v[10:11], v[152:153] op_sel_hi:[1,0]
	v_rcp_f32_e32 v95, v95
	v_pk_mul_f32 v[12:13], v[12:13], v[152:153] op_sel_hi:[1,0]
	v_pk_mul_f32 v[90:91], v[90:91], v[94:95]
	v_rcp_f32_e32 v96, v96
	v_cvt_pk_bf16_f32 v94, v90, v91
	v_pk_mul_f32 v[2:3], v[2:3], v[152:153] op_sel_hi:[1,0]
	v_rcp_f32_e32 v97, v97
	v_pk_mul_f32 v[4:5], v[4:5], v[152:153] op_sel_hi:[1,0]
	v_pk_mul_f32 v[92:93], v[92:93], v[96:97]
	v_rcp_f32_e32 v86, v86
	v_cvt_pk_bf16_f32 v95, v92, v93
	v_rcp_f32_e32 v87, v87
	v_rcp_f32_e32 v88, v88
	v_pk_mul_f32 v[82:83], v[82:83], v[86:87]
	v_rcp_f32_e32 v89, v89
	v_cvt_pk_bf16_f32 v96, v82, v83
	v_pk_mul_f32 v[84:85], v[84:85], v[88:89]
	v_exp_f32_e32 v46, v46
	v_cvt_pk_bf16_f32 v97, v84, v85
	global_store_dwordx4 v[156:157], v[94:97], off
	v_exp_f32_e32 v47, v47
	v_lshl_add_u64 v[156:157], v[156:157], 0, s[4:5]
	v_pk_add_f32 v[46:47], v[46:47], v[140:141]
	v_exp_f32_e32 v48, v48
	s_mov_b32 s4, 0xdc000
	v_exp_f32_e32 v49, v49
	v_exp_f32_e32 v38, v38
	v_pk_add_f32 v[48:49], v[48:49], v[140:141]
	v_exp_f32_e32 v39, v39
	v_exp_f32_e32 v40, v40
	v_pk_add_f32 v[38:39], v[38:39], v[140:141]
	v_exp_f32_e32 v41, v41
	v_rcp_f32_e32 v78, v78
	v_pk_add_f32 v[40:41], v[40:41], v[140:141]
	v_rcp_f32_e32 v79, v79
	v_rcp_f32_e32 v80, v80
	v_pk_mul_f32 v[74:75], v[74:75], v[78:79]
	v_rcp_f32_e32 v81, v81
	v_cvt_pk_bf16_f32 v78, v74, v75
	v_pk_mul_f32 v[76:77], v[76:77], v[80:81]
	v_rcp_f32_e32 v70, v70
	v_cvt_pk_bf16_f32 v79, v76, v77
	v_rcp_f32_e32 v71, v71
	v_rcp_f32_e32 v72, v72
	v_pk_mul_f32 v[66:67], v[66:67], v[70:71]
	v_rcp_f32_e32 v73, v73
	v_cvt_pk_bf16_f32 v80, v66, v67
	v_pk_mul_f32 v[68:69], v[68:69], v[72:73]
	v_exp_f32_e32 v30, v30
	v_cvt_pk_bf16_f32 v81, v68, v69
	global_store_dwordx4 v[156:157], v[78:81], off
	v_exp_f32_e32 v31, v31
	v_lshl_add_u64 v[156:157], v[156:157], 0, s[4:5]
	v_pk_add_f32 v[30:31], v[30:31], v[140:141]
	v_exp_f32_e32 v32, v32
	s_mov_b32 s4, 0x2c000
	v_exp_f32_e32 v33, v33
	v_exp_f32_e32 v22, v22
	v_pk_add_f32 v[32:33], v[32:33], v[140:141]
	v_exp_f32_e32 v23, v23
	v_exp_f32_e32 v24, v24
	v_pk_add_f32 v[22:23], v[22:23], v[140:141]
	v_exp_f32_e32 v25, v25
	v_rcp_f32_e32 v62, v62
	v_pk_add_f32 v[24:25], v[24:25], v[140:141]
	v_rcp_f32_e32 v63, v63
	v_rcp_f32_e32 v64, v64
	v_pk_mul_f32 v[58:59], v[58:59], v[62:63]
	v_rcp_f32_e32 v65, v65
	v_cvt_pk_bf16_f32 v62, v58, v59
	v_pk_mul_f32 v[60:61], v[60:61], v[64:65]
	v_rcp_f32_e32 v54, v54
	v_cvt_pk_bf16_f32 v63, v60, v61
	v_rcp_f32_e32 v55, v55
	v_rcp_f32_e32 v56, v56
	v_pk_mul_f32 v[50:51], v[50:51], v[54:55]
	v_rcp_f32_e32 v57, v57
	v_cvt_pk_bf16_f32 v64, v50, v51
	v_pk_mul_f32 v[52:53], v[52:53], v[56:57]
	v_exp_f32_e32 v14, v14
	v_cvt_pk_bf16_f32 v65, v52, v53
	global_store_dwordx4 v[156:157], v[62:65], off
	v_exp_f32_e32 v15, v15
	v_lshl_add_u64 v[156:157], v[156:157], 0, s[4:5]
	v_pk_add_f32 v[14:15], v[14:15], v[140:141]
	v_exp_f32_e32 v16, v16
	v_exp_f32_e32 v17, v17
	v_exp_f32_e32 v6, v6
	v_pk_add_f32 v[16:17], v[16:17], v[140:141]
	v_exp_f32_e32 v7, v7
	v_exp_f32_e32 v8, v8
	v_pk_add_f32 v[6:7], v[6:7], v[140:141]
	v_exp_f32_e32 v9, v9
	v_rcp_f32_e32 v46, v46
	v_pk_add_f32 v[8:9], v[8:9], v[140:141]
	v_rcp_f32_e32 v47, v47
	v_rcp_f32_e32 v48, v48
	v_pk_mul_f32 v[42:43], v[42:43], v[46:47]
	v_rcp_f32_e32 v49, v49
	v_cvt_pk_bf16_f32 v46, v42, v43
	v_pk_mul_f32 v[44:45], v[44:45], v[48:49]
	v_rcp_f32_e32 v38, v38
	v_cvt_pk_bf16_f32 v47, v44, v45
	v_rcp_f32_e32 v39, v39
	v_rcp_f32_e32 v40, v40
	v_pk_mul_f32 v[34:35], v[34:35], v[38:39]
	v_rcp_f32_e32 v41, v41
	v_cvt_pk_bf16_f32 v48, v34, v35
	v_pk_mul_f32 v[36:37], v[36:37], v[40:41]
	v_rcp_f32_e32 v30, v30
	v_cvt_pk_bf16_f32 v49, v36, v37
	global_store_dwordx4 v[156:157], v[46:49], off
	v_rcp_f32_e32 v31, v31
	v_lshl_add_u64 v[156:157], v[156:157], 0, s[4:5]
	v_pk_mul_f32 v[26:27], v[26:27], v[30:31]
	v_rcp_f32_e32 v32, v32
	v_cvt_pk_bf16_f32 v30, v26, v27
	v_rcp_f32_e32 v33, v33
	v_rcp_f32_e32 v22, v22
	v_pk_mul_f32 v[28:29], v[28:29], v[32:33]
	v_rcp_f32_e32 v23, v23
	v_cvt_pk_bf16_f32 v31, v28, v29
	v_pk_mul_f32 v[18:19], v[18:19], v[22:23]
	v_rcp_f32_e32 v24, v24
	v_cvt_pk_bf16_f32 v32, v18, v19
	v_rcp_f32_e32 v25, v25
	v_rcp_f32_e32 v14, v14
	v_pk_mul_f32 v[20:21], v[20:21], v[24:25]
	v_rcp_f32_e32 v15, v15
	v_cvt_pk_bf16_f32 v33, v20, v21
	global_store_dwordx4 v[156:157], v[30:33], off
	v_rcp_f32_e32 v16, v16
	v_pk_mul_f32 v[10:11], v[10:11], v[14:15]
	v_lshl_add_u64 v[156:157], v[156:157], 0, s[4:5]
	v_rcp_f32_e32 v17, v17
	v_cvt_pk_bf16_f32 v14, v10, v11
	v_pk_mul_f32 v[12:13], v[12:13], v[16:17]
	v_rcp_f32_e32 v6, v6
	v_cvt_pk_bf16_f32 v15, v12, v13
	v_rcp_f32_e32 v7, v7
	v_rcp_f32_e32 v8, v8
	v_pk_mul_f32 v[2:3], v[2:3], v[6:7]
	v_rcp_f32_e32 v9, v9
	v_cvt_pk_bf16_f32 v16, v2, v3
	v_pk_mul_f32 v[4:5], v[4:5], v[8:9]
	s_nop 0
	v_cvt_pk_bf16_f32 v17, v4, v5
	global_store_dwordx4 v[156:157], v[14:17], off
	s_mov_b64 s[4:5], -1
	s_andn2_b64 vcc, exec, s[8:9]
	s_cbranch_vccnz .LBB0_867
	s_andn2_b64 vcc, exec, s[10:11]
	s_cbranch_vccnz .LBB0_866
	s_barrier
	s_branch .LBB0_866
